# P5/P6 start stagger graded by XCD: XCD k starts k*0.19 us late (eight XCDs spread over one K-tile period)
# baseline (speedup 1.0000x reference)
; #define LAS __attribute__((address_space(3)))
;     DI bool next(int i, Unit& u) const {
;         const long L = (long)i * G + c; if (L >= nwg) return false;
;         int wgid = (int)L; { const int q = nwg / NXCD, r = nwg % NXCD, xcd = wgid % NXCD, off = wgid / NXCD; wgid = (xcd < r ? xcd * (q + 1) : r * (q + 1) + (xcd - r) * q) + off; }
;         const int nig = WGM * nN, gid = wgid / nig, fm = gid * WGM, gsz = (nM - fm) < WGM ? (nM - fm) : WGM;
;         u.pm = fm + ((wgid % nig) % gsz); u.pn = (wgid % nig) / gsz; return true;
; __global__ void __launch_bounds__(512, 2) mega(Params p) {
;     ...
;     if (PH(5)) {
;         pg8::Gemm g; g.A0 = (const bf16_t*)(p.ws + WS_ZG); g.A1 = (const bf16_t*)(p.ws + WS_YB) - 2048; g.B0 = (const bf16_t*)(p.ws + WS_WAT); g.B1 = (const bf16_t*)(p.ws + WS_WBT) - 2048;
;         g.lda = DM; g.ldb = DM; g.M = S; g.N = DM; g.K = 2 * DM; g.ksplit = DM / 64;
;         pg8::StaticOrder so; so.init(g.M, g.N, (int)gridDim.x, (int)blockIdx.x);
;         EpiMergeMid e; e.ws = p.ws;
;         pg8::gemm_phase<EpiMergeMid>((LAS unsigned char*)shm, g, so, e);
.LBB0_431:
	s_or_b64 exec, exec, s[4:5]
	v_cmp_gt_i32_e32 vcc, 6, v0
	v_cmp_lt_i32_e64 s[4:5], 5, v1
	s_and_b64 s[4:5], vcc, s[4:5]
	s_and_saveexec_b64 s[6:7], s[4:5]
	s_cbranch_execz .LBB0_456
	s_and_b32 s90, s2, 7
.Lp5_stl:
	s_cmp_eq_u32 s90, 0
	s_cbranch_scc1 .Lp5_std
	s_sleep 5
	s_sub_u32 s90, s90, 1
	s_branch .Lp5_stl

; #define LAS __attribute__((address_space(3)))
;     DI bool next(int i, Unit& u) const {
;         const long L = (long)i * G + c; if (L >= nwg) return false;
;         int wgid = (int)L; { const int q = nwg / NXCD, r = nwg % NXCD, xcd = wgid % NXCD, off = wgid / NXCD; wgid = (xcd < r ? xcd * (q + 1) : r * (q + 1) + (xcd - r) * q) + off; }
;         const int nig = WGM * nN, gid = wgid / nig, fm = gid * WGM, gsz = (nM - fm) < WGM ? (nM - fm) : WGM;
;         u.pm = fm + ((wgid % nig) % gsz); u.pn = (wgid % nig) / gsz; return true;
; __global__ void __launch_bounds__(512, 2) mega(Params p) {
;     ...
;     if (PH(6)) {
;         pg8::Gemm g; g.A0 = (const bf16_t*)(p.ws + WS_MRG); g.A1 = g.A0; g.B0 = (const bf16_t*)(p.ws + WS_WOT); g.B1 = g.B0;
;         g.lda = DM; g.ldb = DM; g.M = S; g.N = DM; g.K = DM; g.ksplit = DM / 64;
;         pg8::StaticOrder so; so.init(g.M, g.N, (int)gridDim.x, (int)blockIdx.x);
;         EpiOut e; e.ws = p.ws;
;         pg8::gemm_phase<EpiOut>((LAS unsigned char*)shm, g, so, e);
.LBB0_506:
	s_or_b64 exec, exec, s[4:5]
	v_cmp_gt_i32_e32 vcc, 7, v0
	v_cmp_lt_i32_e64 s[4:5], 6, v1
	s_and_b64 s[4:5], vcc, s[4:5]
	s_and_saveexec_b64 s[8:9], s[4:5]
	s_cbranch_execz .LBB0_545
	s_and_b32 s90, s2, 7
